# v6 + P3 tail weight-conversion slice split between the Hyena-first workgroup (round 0) and its attention-first partner (round 1)
# speedup vs baseline: 1.0008x; 1.0008x over previous
.LBB0_784:
	s_movk_i32 s24, 0x800
	s_movk_i32 s22, 0x400
	s_mov_b64 s[20:21], s[0:1]
	s_mov_b32 s35, 1
	s_cbranch_execz .LBB0_771
	s_branch .LBB0_772
.LBB0_785:
	s_branch .LBB0_1006
.LBB0_786:
	s_and_b64 vcc, exec, s[0:1]
	s_cbranch_vccz .LBB0_1064
	v_readlane_b32 s0, v252, 0
	s_cmpk_lt_u32 s0, 0x100
	s_cselect_b64 s[2:3], -1, 0
	s_cmpk_gt_u32 s0, 0xff
	s_cselect_b64 s[0:1], -1, 0
	s_waitcnt lgkmcnt(0)
	s_not_b32 s4, s85
	s_lshr_b32 s4, s4, 2
	s_and_b64 s[0:1], s[74:75], s[0:1]
	s_and_b32 s4, s4, 32
	s_and_b64 s[0:1], s[0:1], exec
	v_readlane_b32 s1, v252, 39
	s_cselect_b32 s14, s4, 0
	s_lshl_b32 s1, s1, 5
	s_lshl_b32 s0, s96, 7
	s_and_b32 s1, s1, 0x60
	s_or_b32 s0, s0, s1
	s_add_i32 s15, s0, 0x1e80
	s_and_b32 s33, s85, 3
	s_cmp_eq_u32 s33, 2
	s_mov_b32 s4, 0
	s_cbranch_scc1 .LBB0_908
	v_sub_u32_e32 v1, 0x63f, v0
	s_waitcnt vmcnt(0)
	v_lshrrev_b32_e32 v2, 9, v1
	v_or_b32_e32 v1, 0x200, v0
	v_mov_b32_e32 v3, v2
	s_mov_b64 s[8:9], 0
	s_mov_b32 s5, 1
	s_mov_b32 s12, 0x51eb851f
	s_movk_i32 s13, 0x320
	s_movk_i32 s16, 0x64
	v_mov_b32_e32 v6, 0x8c80
	s_movk_i32 s17, 0x1190
	v_mov_b32_e32 v7, 0
	s_mov_b32 s10, s4
	v_mov_b64_e32 v[4:5], v[0:1]
	s_branch .LBB0_790

.LBB0_1006:
	s_andn2_b64 vcc, exec, s[74:75]
	s_cbranch_vccnz .LBB0_1064
	s_lshr_b32 s0, s96, 1
	s_and_b32 s0, s0, 0x7fffff8
	s_and_b32 s1, s96, 7
	s_or_b32 s0, s0, s1
	v_readlane_b32 s1, v252, 39
	s_lshl_b32 s0, s0, 5
	s_lshl_b32 s1, s1, 2
	s_add_i32 s33, s1, s0
	s_add_i32 s33, s33, 0x9e80
	s_lshl_b32 s0, s33, 1
	s_and_b32 s64, s0, 0x1fc0
	v_readlane_b32 s0, v252, 42
	s_add_i32 s62, s64, 0xffffeb00
	s_add_i32 s63, s64, 0xffffed00
	s_addk_i32 s64, 0xef00
	v_readlane_b32 s2, v252, 44
	v_readlane_b32 s14, v252, 56
	v_readlane_b32 s3, v252, 45
	v_readlane_b32 s15, v252, 57
	s_add_u32 s2, s14, 0x9c00000
	s_addc_u32 s3, s15, 0
	s_add_u32 s36, s14, 0x1c00000
	s_addc_u32 s37, s15, 0
	s_add_u32 s50, s14, 0x1900000
	s_addc_u32 s51, s15, 0
	s_add_u32 s86, s14, 0x1800000
	s_addc_u32 s87, s15, 0
	s_add_u32 s90, s14, 0x1700000
	s_addc_u32 s91, s15, 0
	s_add_u32 s92, s14, 0x6c00000
	s_addc_u32 s93, s15, 0
	s_add_u32 s94, s14, 0xe00000
	s_addc_u32 s95, s15, 0
	v_readlane_b32 s1, v252, 43
	s_cmpk_lt_u32 s33, 0xcc80
	s_cselect_b64 s[0:1], -1, 0
	s_cmpk_gt_u32 s33, 0x87f
	v_lshlrev_b32_e32 v1, 3, v0
	s_cselect_b64 s[68:69], -1, 0
	s_cmpk_gt_u32 s33, 0x97f
	v_and_b32_e32 v66, 56, v1
	v_lshrrev_b32_e32 v1, 1, v0
	s_cselect_b64 s[70:71], -1, 0
	s_cmpk_gt_u32 s33, 0xa7f
	v_and_b32_e32 v68, 28, v1
	v_mov_b32_e32 v71, 0
	s_cselect_b64 s[20:21], -1, 0
	s_cmpk_gt_u32 s33, 0xc7f
	v_cndmask_b32_e64 v1, 0, 1, s[0:1]
	v_mov_b32_e32 v67, v71
	s_mov_b32 s27, 0
	s_mov_b64 s[24:25], 0
	s_cselect_b64 s[22:23], -1, 0
	v_cmp_ne_u32_e64 s[0:1], 1, v1
	v_lshlrev_b32_e32 v72, 2, v68
	v_mov_b32_e32 v73, v71
	v_readlane_b32 s4, v252, 46
	v_readlane_b32 s5, v252, 47
	v_readlane_b32 s6, v252, 48
	v_readlane_b32 s7, v252, 49
	v_readlane_b32 s8, v252, 50
	v_readlane_b32 s9, v252, 51
	v_readlane_b32 s10, v252, 52
	v_readlane_b32 s11, v252, 53
	v_readlane_b32 s12, v252, 54
	v_readlane_b32 s13, v252, 55
	s_bfe_u32 s27, s96, 0x10003
	s_lshl_b32 s27, s27, 1
	s_branch .LBB0_1010
